# odd attention softmax s0: subtract and exp batched (no dependent sub-exp chain)
# speedup vs baseline: 1.0106x; 1.0045x over previous
.LBB0_432:
	v_sub_f32_e32 v112, v112, v165
	v_sub_f32_e32 v116, v116, v165
	v_sub_f32_e32 v114, v114, v165
	v_sub_f32_e32 v115, v115, v165
	v_sub_f32_e32 v160, v160, v165
	v_sub_f32_e32 v164, v164, v165
	v_sub_f32_e32 v113, v113, v165
	v_sub_f32_e32 v163, v163, v165
	v_sub_f32_e32 v159, v159, v165
	v_sub_f32_e32 v158, v158, v165
	v_sub_f32_e32 v162, v162, v165
	v_sub_f32_e32 v161, v161, v165
	v_sub_f32_e32 v157, v157, v165
	v_sub_f32_e32 v118, v118, v165
	v_sub_f32_e32 v119, v119, v165
	v_sub_f32_e32 v117, v117, v165
	v_exp_f32_e32 v167, v112
	v_exp_f32_e32 v168, v116
	v_exp_f32_e32 v169, v114
	v_exp_f32_e32 v170, v115
	v_exp_f32_e32 v171, v160
	v_exp_f32_e32 v172, v164
	v_exp_f32_e32 v166, v113
	v_exp_f32_e32 v173, v163
	v_exp_f32_e32 v174, v159
	v_exp_f32_e32 v175, v158
	v_exp_f32_e32 v176, v162
	v_exp_f32_e32 v177, v161
	v_exp_f32_e32 v178, v157
	v_exp_f32_e32 v179, v118
	v_exp_f32_e32 v180, v119
	v_exp_f32_e32 v181, v117
	s_nop 0
	v_cvt_pk_bf16_f32 v217, v168, v169
	v_cvt_pk_bf16_f32 v218, v170, v171
	v_cvt_pk_bf16_f32 v216, v166, v167
	v_cvt_pk_bf16_f32 v219, v172, v173
	v_cvt_pk_bf16_f32 v220, v174, v175
	v_cvt_pk_bf16_f32 v221, v176, v177
	v_cvt_pk_bf16_f32 v222, v178, v179
	v_cvt_pk_bf16_f32 v223, v180, v181
	ds_read_b128 v[112:115], v153 offset:128
	ds_read_b128 v[116:119], v153 offset:192
	s_waitcnt lgkmcnt(1)
	v_mfma_f32_16x16x32_bf16 v[112:115], v[112:115], v[8:11], 0
	ds_read_b128 v[158:161], v153 offset:4736
	ds_read_b128 v[162:165], v153 offset:9344
	ds_read_b128 v[182:185], v153 offset:13952
	s_waitcnt lgkmcnt(3)
	v_mfma_f32_16x16x32_bf16 v[112:115], v[116:119], v[12:15], v[112:115]
	ds_read_b128 v[116:119], v153 offset:4800
	s_waitcnt lgkmcnt(3)
	v_mfma_f32_16x16x32_bf16 v[158:161], v[158:161], v[8:11], 0
	s_waitcnt lgkmcnt(0)
	v_mfma_f32_16x16x32_bf16 v[116:119], v[116:119], v[12:15], v[158:161]
	s_nop 5
	ds_read_b128 v[158:161], v153 offset:9408
	v_mfma_f32_16x16x32_bf16 v[162:165], v[162:165], v[8:11], 0
	s_waitcnt lgkmcnt(0)
	v_mfma_f32_16x16x32_bf16 v[186:189], v[158:161], v[12:15], v[162:165]
	ds_read_b128 v[158:161], v153 offset:14016
	s_nop 6
	v_mul_f32_e32 v157, 0x3e38aa3b, v186
	v_mfma_f32_16x16x32_bf16 v[162:165], v[182:185], v[8:11], 0
	s_waitcnt lgkmcnt(0)
	v_mfma_f32_16x16x32_bf16 v[182:185], v[158:161], v[12:15], v[162:165]
	v_mul_f32_e32 v161, 0x3e38aa3b, v116
	v_mul_f32_e32 v159, 0x3e38aa3b, v117
	s_nop 3
	v_mul_f32_e32 v165, 0x3e38aa3b, v112
	v_mul_f32_e32 v163, 0x3e38aa3b, v113
	v_max3_f32 v112, v165, s30, v163
	v_mul_f32_e32 v164, 0x3e38aa3b, v114
	v_mul_f32_e32 v162, 0x3e38aa3b, v115
	v_max3_f32 v112, v112, v164, v162
	v_max3_f32 v112, v112, v161, v159
	v_mul_f32_e32 v160, 0x3e38aa3b, v118
	v_mul_f32_e32 v158, 0x3e38aa3b, v119
	v_max3_f32 v112, v112, v160, v158
	v_mul_f32_e32 v118, 0x3e38aa3b, v187
	v_max3_f32 v112, v112, v157, v118
	v_mul_f32_e32 v119, 0x3e38aa3b, v188
	v_mul_f32_e32 v117, 0x3e38aa3b, v189
	v_max3_f32 v112, v112, v119, v117
	v_mul_f32_e32 v115, 0x3e38aa3b, v182
	v_mul_f32_e32 v113, 0x3e38aa3b, v183
	v_max3_f32 v116, v112, v115, v113
	v_mul_f32_e32 v114, 0x3e38aa3b, v184
	v_mul_f32_e32 v112, 0x3e38aa3b, v185
	v_max3_f32 v116, v116, v114, v112
	v_mov_b32_e32 v182, v116
	s_nop 1
	v_permlane16_swap_b32_e32 v116, v182
	v_max_f32_e32 v182, v182, v182
	v_max_f32_e32 v116, v116, v116
	v_max_f32_e32 v116, v116, v182
	v_mov_b32_e32 v182, v116
	s_nop 1
	v_permlane32_swap_b32_e32 v116, v182
	v_max3_f32 v116, v156, v116, v182
	v_cmp_gt_f32_e32 vcc, v116, v156
	s_cbranch_vccz .LBB0_434
	v_sub_f32_e32 v156, v156, v116
	v_exp_f32_e32 v156, v156
	s_nop 0
	v_mul_f32_e32 v121, v121, v156
	v_pk_mul_f32 v[94:95], v[94:95], v[156:157] op_sel_hi:[1,0]
	v_pk_mul_f32 v[92:93], v[92:93], v[156:157] op_sel_hi:[1,0]
	v_pk_mul_f32 v[90:91], v[90:91], v[156:157] op_sel_hi:[1,0]
	v_pk_mul_f32 v[88:89], v[88:89], v[156:157] op_sel_hi:[1,0]
	v_pk_mul_f32 v[58:59], v[58:59], v[156:157] op_sel_hi:[1,0]
	v_pk_mul_f32 v[56:57], v[56:57], v[156:157] op_sel_hi:[1,0]
	v_pk_mul_f32 v[50:51], v[50:51], v[156:157] op_sel_hi:[1,0]
	v_pk_mul_f32 v[48:49], v[48:49], v[156:157] op_sel_hi:[1,0]
	v_pk_mul_f32 v[66:67], v[66:67], v[156:157] op_sel_hi:[1,0]
	v_pk_mul_f32 v[64:65], v[64:65], v[156:157] op_sel_hi:[1,0]
	v_pk_mul_f32 v[74:75], v[74:75], v[156:157] op_sel_hi:[1,0]
	v_pk_mul_f32 v[72:73], v[72:73], v[156:157] op_sel_hi:[1,0]
	v_pk_mul_f32 v[62:63], v[62:63], v[156:157] op_sel_hi:[1,0]
	v_pk_mul_f32 v[60:61], v[60:61], v[156:157] op_sel_hi:[1,0]
	v_pk_mul_f32 v[106:107], v[106:107], v[156:157] op_sel_hi:[1,0]
	v_pk_mul_f32 v[104:105], v[104:105], v[156:157] op_sel_hi:[1,0]
	v_mov_b32_e32 v156, v116
